# GEMM K-loop trimmed: duplicate lgkmcnt waits and M0-hazard nops removed (address computation placed between M0 write and LDS-DMA load), one A-fragment LDS base with immediate offsets, folded stage con
# speedup vs baseline: 1.0202x; 1.0035x over previous
.LBB0_760:
	s_add_i32 s38, s46, 2
	s_add_u32 s8, s26, s4
	s_addc_u32 s9, s27, s5
	s_add_u32 s8, s8, 0x100
	s_addc_u32 s9, s9, 0
	s_add_u32 s30, s44, s4
	s_addc_u32 s31, s45, s5
	v_add_u32_e32 v252, 0x10000, v193
	ds_read_b128 v[132:135], v252
	ds_read_b128 v[136:139], v252 offset:1024
	ds_read_b128 v[140:143], v252 offset:2048
	ds_read_b128 v[144:147], v252 offset:3072
	s_cmp_eq_u32 s71, s46
	s_cselect_b32 s9, s13, s9
	s_cselect_b32 s8, s12, s8
	s_cselect_b32 s31, s57, s31
	s_cselect_b32 s30, s56, s30
	v_lshl_add_u64 v[190:191], v[128:129], 0, s[4:5]
	s_add_i32 m0, s19, 0xc000
	ds_read_b128 v[148:151], v202
	ds_read_b128 v[152:155], v202 offset:1024
	ds_read_b128 v[156:159], v202 offset:2048
	ds_read_b128 v[160:163], v202 offset:3072
	ds_read_b128 v[164:167], v202 offset:4096
	ds_read_b128 v[204:207], v202 offset:5120
	ds_read_b128 v[208:211], v202 offset:6144
	ds_read_b128 v[212:215], v202 offset:7168
	global_load_lds_dwordx4 v[190:191], off
	s_add_i32 m0, s19, 0xe000
	v_lshl_add_u64 v[190:191], v[130:131], 0, s[4:5]
	global_load_lds_dwordx4 v[190:191], off
	s_waitcnt lgkmcnt(8)
	s_barrier
	s_waitcnt lgkmcnt(0)
	v_mfma_f32_16x16x32_bf16 v[124:127], v[132:135], v[148:151], v[124:127]
	v_mfma_f32_16x16x32_bf16 v[120:123], v[140:143], v[148:151], v[120:123]
	v_mfma_f32_16x16x32_bf16 v[108:111], v[132:135], v[156:159], v[108:111]
	v_mfma_f32_16x16x32_bf16 v[104:107], v[140:143], v[156:159], v[104:107]
	v_mfma_f32_16x16x32_bf16 v[92:95], v[132:135], v[164:167], v[92:95]
	v_mfma_f32_16x16x32_bf16 v[88:91], v[140:143], v[164:167], v[88:91]
	v_mfma_f32_16x16x32_bf16 v[76:79], v[132:135], v[208:211], v[76:79]
	v_mfma_f32_16x16x32_bf16 v[72:75], v[140:143], v[208:211], v[72:75]
	v_mfma_f32_16x16x32_bf16 v[124:127], v[136:139], v[152:155], v[124:127]
	v_mfma_f32_16x16x32_bf16 v[120:123], v[144:147], v[152:155], v[120:123]
	v_mfma_f32_16x16x32_bf16 v[108:111], v[136:139], v[160:163], v[108:111]
	v_mfma_f32_16x16x32_bf16 v[104:107], v[144:147], v[160:163], v[104:107]
	v_mfma_f32_16x16x32_bf16 v[92:95], v[136:139], v[204:207], v[92:95]
	v_mfma_f32_16x16x32_bf16 v[88:91], v[144:147], v[204:207], v[88:91]
	v_mfma_f32_16x16x32_bf16 v[76:79], v[136:139], v[212:215], v[76:79]
	v_mfma_f32_16x16x32_bf16 v[72:75], v[144:147], v[212:215], v[72:75]
	s_barrier
	s_add_i32 s47, s53, 0x10000
	ds_read_b128 v[216:219], v252 offset:16384
	ds_read_b128 v[220:223], v252 offset:17408
	ds_read_b128 v[232:235], v252 offset:18432
	ds_read_b128 v[240:243], v252 offset:19456
	s_mov_b32 m0, s47
	v_lshl_add_u64 v[190:191], s[30:31], 0, v[180:181]
	global_load_lds_dwordx4 v[190:191], off
	s_add_i32 m0, s47, 0x2000
	v_lshl_add_u64 v[224:225], s[30:31], 0, v[176:177]
	global_load_lds_dwordx4 v[224:225], off
	s_barrier
	s_waitcnt lgkmcnt(0)
	v_mfma_f32_16x16x32_bf16 v[116:119], v[216:219], v[148:151], v[116:119]
	v_mfma_f32_16x16x32_bf16 v[112:115], v[232:235], v[148:151], v[112:115]
	v_mfma_f32_16x16x32_bf16 v[100:103], v[216:219], v[156:159], v[100:103]
	v_mfma_f32_16x16x32_bf16 v[96:99], v[232:235], v[156:159], v[96:99]
	v_mfma_f32_16x16x32_bf16 v[84:87], v[216:219], v[164:167], v[84:87]
	v_mfma_f32_16x16x32_bf16 v[80:83], v[232:235], v[164:167], v[80:83]
	v_mfma_f32_16x16x32_bf16 v[68:71], v[216:219], v[208:211], v[68:71]
	v_mfma_f32_16x16x32_bf16 v[64:67], v[232:235], v[208:211], v[64:67]
	v_mfma_f32_16x16x32_bf16 v[116:119], v[220:223], v[152:155], v[116:119]
	v_mfma_f32_16x16x32_bf16 v[112:115], v[240:243], v[152:155], v[112:115]
	v_mfma_f32_16x16x32_bf16 v[100:103], v[220:223], v[160:163], v[100:103]
	v_mfma_f32_16x16x32_bf16 v[96:99], v[240:243], v[160:163], v[96:99]
	v_mfma_f32_16x16x32_bf16 v[84:87], v[220:223], v[204:207], v[84:87]
	v_mfma_f32_16x16x32_bf16 v[80:83], v[240:243], v[204:207], v[80:83]
	v_mfma_f32_16x16x32_bf16 v[68:71], v[220:223], v[212:215], v[68:71]
	v_mfma_f32_16x16x32_bf16 v[64:67], v[240:243], v[212:215], v[64:67]
	s_mov_b32 m0, s19
	v_lshl_add_u64 v[244:245], s[8:9], 0, v[178:179]
	s_barrier
	ds_read_b128 v[148:151], v202 offset:16384
	ds_read_b128 v[152:155], v202 offset:17408
	ds_read_b128 v[156:159], v202 offset:18432
	ds_read_b128 v[160:163], v202 offset:19456
	ds_read_b128 v[164:167], v202 offset:20480
	ds_read_b128 v[204:207], v202 offset:21504
	ds_read_b128 v[208:211], v202 offset:22528
	ds_read_b128 v[212:215], v202 offset:23552
	global_load_lds_dwordx4 v[244:245], off
	s_mov_b32 m0, s21
	v_lshl_add_u64 v[246:247], s[8:9], 0, v[174:175]
	global_load_lds_dwordx4 v[246:247], off
	s_barrier
	s_waitcnt lgkmcnt(0)
	v_mfma_f32_16x16x32_bf16 v[60:63], v[132:135], v[148:151], v[60:63]
	v_mfma_f32_16x16x32_bf16 v[56:59], v[140:143], v[148:151], v[56:59]
	v_mfma_f32_16x16x32_bf16 v[44:47], v[132:135], v[156:159], v[44:47]
	v_mfma_f32_16x16x32_bf16 v[40:43], v[140:143], v[156:159], v[40:43]
	v_mfma_f32_16x16x32_bf16 v[28:31], v[132:135], v[164:167], v[28:31]
	v_mfma_f32_16x16x32_bf16 v[24:27], v[140:143], v[164:167], v[24:27]
	v_mfma_f32_16x16x32_bf16 v[12:15], v[132:135], v[208:211], v[12:15]
	v_mfma_f32_16x16x32_bf16 v[8:11], v[140:143], v[208:211], v[8:11]
	v_mfma_f32_16x16x32_bf16 v[60:63], v[136:139], v[152:155], v[60:63]
	v_mfma_f32_16x16x32_bf16 v[56:59], v[144:147], v[152:155], v[56:59]
	v_mfma_f32_16x16x32_bf16 v[44:47], v[136:139], v[160:163], v[44:47]
	v_mfma_f32_16x16x32_bf16 v[40:43], v[144:147], v[160:163], v[40:43]
	v_mfma_f32_16x16x32_bf16 v[28:31], v[136:139], v[204:207], v[28:31]
	v_mfma_f32_16x16x32_bf16 v[24:27], v[144:147], v[204:207], v[24:27]
	v_mfma_f32_16x16x32_bf16 v[12:15], v[136:139], v[212:215], v[12:15]
	v_mfma_f32_16x16x32_bf16 v[8:11], v[144:147], v[212:215], v[8:11]
	s_barrier
	s_add_u32 s30, s30, s90
	s_addc_u32 s31, s31, s91
	s_add_i32 s46, s53, 0x14000
	s_mov_b32 m0, s46
	v_lshl_add_u64 v[248:249], s[30:31], 0, v[180:181]
	global_load_lds_dwordx4 v[248:249], off
	s_add_i32 m0, s46, 0x2000
	v_lshl_add_u64 v[250:251], s[30:31], 0, v[176:177]
	global_load_lds_dwordx4 v[250:251], off
	s_waitcnt vmcnt(6)
	s_barrier
	v_mfma_f32_16x16x32_bf16 v[52:55], v[216:219], v[148:151], v[52:55]
	v_mfma_f32_16x16x32_bf16 v[48:51], v[232:235], v[148:151], v[48:51]
	v_mfma_f32_16x16x32_bf16 v[36:39], v[216:219], v[156:159], v[36:39]
	v_mfma_f32_16x16x32_bf16 v[32:35], v[232:235], v[156:159], v[32:35]
	v_mfma_f32_16x16x32_bf16 v[20:23], v[216:219], v[164:167], v[20:23]
	v_mfma_f32_16x16x32_bf16 v[16:19], v[232:235], v[164:167], v[16:19]
	v_mfma_f32_16x16x32_bf16 v[4:7], v[216:219], v[208:211], v[4:7]
	v_mfma_f32_16x16x32_bf16 v[0:3], v[232:235], v[208:211], v[0:3]
	v_mfma_f32_16x16x32_bf16 v[52:55], v[220:223], v[152:155], v[52:55]
	v_mfma_f32_16x16x32_bf16 v[48:51], v[240:243], v[152:155], v[48:51]
	v_mfma_f32_16x16x32_bf16 v[36:39], v[220:223], v[160:163], v[36:39]
	v_mfma_f32_16x16x32_bf16 v[32:35], v[240:243], v[160:163], v[32:35]
	v_mfma_f32_16x16x32_bf16 v[20:23], v[220:223], v[204:207], v[20:23]
	v_mfma_f32_16x16x32_bf16 v[16:19], v[240:243], v[204:207], v[16:19]
	v_mfma_f32_16x16x32_bf16 v[4:7], v[220:223], v[212:215], v[4:7]
	v_mfma_f32_16x16x32_bf16 v[0:3], v[240:243], v[212:215], v[0:3]
	s_barrier
	ds_read_b128 v[132:135], v252 offset:32768
	ds_read_b128 v[136:139], v252 offset:33792
	ds_read_b128 v[140:143], v252 offset:34816
	ds_read_b128 v[144:147], v252 offset:35840
	s_add_u32 s8, s8, s22
	s_addc_u32 s9, s9, s23
	s_mov_b32 m0, s64
	v_lshl_add_u64 v[216:217], s[8:9], 0, v[178:179]
	ds_read_b128 v[148:151], v202 offset:32768
	ds_read_b128 v[152:155], v202 offset:33792
	ds_read_b128 v[156:159], v202 offset:34816
	ds_read_b128 v[160:163], v202 offset:35840
	ds_read_b128 v[164:167], v202 offset:36864
	ds_read_b128 v[204:207], v202 offset:37888
	ds_read_b128 v[208:211], v202 offset:38912
	ds_read_b128 v[212:215], v202 offset:39936
	global_load_lds_dwordx4 v[216:217], off
	s_mov_b32 m0, s65
	v_lshl_add_u64 v[216:217], s[8:9], 0, v[174:175]
	global_load_lds_dwordx4 v[216:217], off
	s_waitcnt lgkmcnt(8)
	s_barrier
	s_waitcnt lgkmcnt(0)
	v_mfma_f32_16x16x32_bf16 v[124:127], v[132:135], v[148:151], v[124:127]
	v_mfma_f32_16x16x32_bf16 v[120:123], v[140:143], v[148:151], v[120:123]
	v_mfma_f32_16x16x32_bf16 v[108:111], v[132:135], v[156:159], v[108:111]
	v_mfma_f32_16x16x32_bf16 v[104:107], v[140:143], v[156:159], v[104:107]
	v_mfma_f32_16x16x32_bf16 v[92:95], v[132:135], v[164:167], v[92:95]
	v_mfma_f32_16x16x32_bf16 v[88:91], v[140:143], v[164:167], v[88:91]
	v_mfma_f32_16x16x32_bf16 v[76:79], v[132:135], v[208:211], v[76:79]
	v_mfma_f32_16x16x32_bf16 v[72:75], v[140:143], v[208:211], v[72:75]
	v_mfma_f32_16x16x32_bf16 v[124:127], v[136:139], v[152:155], v[124:127]
	v_mfma_f32_16x16x32_bf16 v[120:123], v[144:147], v[152:155], v[120:123]
	v_mfma_f32_16x16x32_bf16 v[108:111], v[136:139], v[160:163], v[108:111]
	v_mfma_f32_16x16x32_bf16 v[104:107], v[144:147], v[160:163], v[104:107]
	v_mfma_f32_16x16x32_bf16 v[92:95], v[136:139], v[204:207], v[92:95]
	v_mfma_f32_16x16x32_bf16 v[88:91], v[144:147], v[204:207], v[88:91]
	v_mfma_f32_16x16x32_bf16 v[76:79], v[136:139], v[212:215], v[76:79]
	v_mfma_f32_16x16x32_bf16 v[72:75], v[144:147], v[212:215], v[72:75]
	s_barrier
	s_add_i32 s9, s77, s53
	v_lshl_add_u64 v[190:191], v[190:191], 0, s[58:59]
	s_mov_b32 m0, s9
	ds_read_b128 v[216:219], v252 offset:49152
	ds_read_b128 v[220:223], v252 offset:50176
	ds_read_b128 v[232:235], v252 offset:51200
	ds_read_b128 v[240:243], v252 offset:52224
	global_load_lds_dwordx4 v[190:191], off
	s_add_i32 m0, s9, 0x2000
	v_lshl_add_u64 v[190:191], v[224:225], 0, s[58:59]
	global_load_lds_dwordx4 v[190:191], off
	s_barrier
	s_waitcnt lgkmcnt(0)
	v_mfma_f32_16x16x32_bf16 v[116:119], v[216:219], v[148:151], v[116:119]
	v_mfma_f32_16x16x32_bf16 v[112:115], v[232:235], v[148:151], v[112:115]
	v_mfma_f32_16x16x32_bf16 v[100:103], v[216:219], v[156:159], v[100:103]
	v_mfma_f32_16x16x32_bf16 v[96:99], v[232:235], v[156:159], v[96:99]
	v_mfma_f32_16x16x32_bf16 v[84:87], v[216:219], v[164:167], v[84:87]
	v_mfma_f32_16x16x32_bf16 v[80:83], v[232:235], v[164:167], v[80:83]
	v_mfma_f32_16x16x32_bf16 v[68:71], v[216:219], v[208:211], v[68:71]
	v_mfma_f32_16x16x32_bf16 v[64:67], v[232:235], v[208:211], v[64:67]
	v_mfma_f32_16x16x32_bf16 v[116:119], v[220:223], v[152:155], v[116:119]
	v_mfma_f32_16x16x32_bf16 v[112:115], v[240:243], v[152:155], v[112:115]
	v_mfma_f32_16x16x32_bf16 v[100:103], v[220:223], v[160:163], v[100:103]
	v_mfma_f32_16x16x32_bf16 v[96:99], v[240:243], v[160:163], v[96:99]
	v_mfma_f32_16x16x32_bf16 v[84:87], v[220:223], v[204:207], v[84:87]
	v_mfma_f32_16x16x32_bf16 v[80:83], v[240:243], v[204:207], v[80:83]
	v_mfma_f32_16x16x32_bf16 v[68:71], v[220:223], v[212:215], v[68:71]
	v_mfma_f32_16x16x32_bf16 v[64:67], v[240:243], v[212:215], v[64:67]
	s_mov_b32 m0, s66
	v_lshl_add_u64 v[190:191], v[244:245], 0, s[58:59]
	s_barrier
	ds_read_b128 v[148:151], v202 offset:49152
	ds_read_b128 v[152:155], v202 offset:50176
	ds_read_b128 v[156:159], v202 offset:51200
	ds_read_b128 v[160:163], v202 offset:52224
	ds_read_b128 v[164:167], v202 offset:53248
	ds_read_b128 v[204:207], v202 offset:54272
	ds_read_b128 v[208:211], v202 offset:55296
	ds_read_b128 v[212:215], v202 offset:56320
	global_load_lds_dwordx4 v[190:191], off
	s_mov_b32 m0, s67
	v_lshl_add_u64 v[190:191], v[246:247], 0, s[58:59]
	global_load_lds_dwordx4 v[190:191], off
	s_barrier
	s_waitcnt lgkmcnt(0)
	v_mfma_f32_16x16x32_bf16 v[60:63], v[132:135], v[148:151], v[60:63]
	v_mfma_f32_16x16x32_bf16 v[56:59], v[140:143], v[148:151], v[56:59]
	v_mfma_f32_16x16x32_bf16 v[44:47], v[132:135], v[156:159], v[44:47]
	v_mfma_f32_16x16x32_bf16 v[40:43], v[140:143], v[156:159], v[40:43]
	v_mfma_f32_16x16x32_bf16 v[28:31], v[132:135], v[164:167], v[28:31]
	v_mfma_f32_16x16x32_bf16 v[24:27], v[140:143], v[164:167], v[24:27]
	v_mfma_f32_16x16x32_bf16 v[12:15], v[132:135], v[208:211], v[12:15]
	v_mfma_f32_16x16x32_bf16 v[8:11], v[140:143], v[208:211], v[8:11]
	v_mfma_f32_16x16x32_bf16 v[60:63], v[136:139], v[152:155], v[60:63]
	v_mfma_f32_16x16x32_bf16 v[56:59], v[144:147], v[152:155], v[56:59]
	v_mfma_f32_16x16x32_bf16 v[44:47], v[136:139], v[160:163], v[44:47]
	v_mfma_f32_16x16x32_bf16 v[40:43], v[144:147], v[160:163], v[40:43]
	v_mfma_f32_16x16x32_bf16 v[28:31], v[136:139], v[204:207], v[28:31]
	v_mfma_f32_16x16x32_bf16 v[24:27], v[144:147], v[204:207], v[24:27]
	v_mfma_f32_16x16x32_bf16 v[12:15], v[136:139], v[212:215], v[12:15]
	v_mfma_f32_16x16x32_bf16 v[8:11], v[144:147], v[212:215], v[8:11]
	s_barrier
	s_add_i32 s8, s53, 0x1c000
	s_mov_b32 m0, s8
	v_lshl_add_u64 v[132:133], v[248:249], 0, s[58:59]
	global_load_lds_dwordx4 v[132:133], off
	s_add_i32 m0, s8, 0x2000
	v_lshl_add_u64 v[132:133], v[250:251], 0, s[58:59]
	global_load_lds_dwordx4 v[132:133], off
	s_waitcnt vmcnt(6)
	s_barrier
	v_mfma_f32_16x16x32_bf16 v[52:55], v[216:219], v[148:151], v[52:55]
	v_mfma_f32_16x16x32_bf16 v[48:51], v[232:235], v[148:151], v[48:51]
	v_mfma_f32_16x16x32_bf16 v[36:39], v[216:219], v[156:159], v[36:39]
	v_mfma_f32_16x16x32_bf16 v[32:35], v[232:235], v[156:159], v[32:35]
	v_mfma_f32_16x16x32_bf16 v[20:23], v[216:219], v[164:167], v[20:23]
	v_mfma_f32_16x16x32_bf16 v[16:19], v[232:235], v[164:167], v[16:19]
	v_mfma_f32_16x16x32_bf16 v[4:7], v[216:219], v[208:211], v[4:7]
	v_mfma_f32_16x16x32_bf16 v[0:3], v[232:235], v[208:211], v[0:3]
	v_mfma_f32_16x16x32_bf16 v[52:55], v[220:223], v[152:155], v[52:55]
	v_mfma_f32_16x16x32_bf16 v[48:51], v[240:243], v[152:155], v[48:51]
	v_mfma_f32_16x16x32_bf16 v[36:39], v[220:223], v[160:163], v[36:39]
	v_mfma_f32_16x16x32_bf16 v[32:35], v[240:243], v[160:163], v[32:35]
	v_mfma_f32_16x16x32_bf16 v[20:23], v[220:223], v[204:207], v[20:23]
	v_mfma_f32_16x16x32_bf16 v[16:19], v[240:243], v[204:207], v[16:19]
	v_mfma_f32_16x16x32_bf16 v[4:7], v[220:223], v[212:215], v[4:7]
	v_mfma_f32_16x16x32_bf16 v[0:3], v[240:243], v[212:215], v[0:3]
	s_add_u32 s4, s4, 0x100
	s_addc_u32 s5, s5, 0
	s_cmp_ge_i32 s38, s68
	s_barrier
	s_cbranch_scc1 .Lkx_exit
	s_mov_b32 s46, s38
	s_andn2_b64 vcc, exec, s[96:97]
	s_cbranch_vccnz .LBB0_760
	s_branch .LBB0_754
.Lkx_exit:
	s_load_dwordx2 s[26:27], s[0:1], 0x150
	s_mov_b64 s[4:5], -1
	s_mov_b64 s[8:9], 0
	s_cmp_lt_i32 s50, 5
	s_mov_b64 s[44:45], 0
	s_cbranch_scc1 .LBB0_785
	s_cmp_gt_i32 s50, 7
	s_cbranch_scc0 .LBB0_775
	s_cmp_gt_i32 s50, 8
	s_cbranch_scc0 .LBB0_772
	s_cmp_gt_i32 s50, 10
	s_cbranch_scc0 .LBB0_768
	s_cmp_eq_u32 s50, 11
	s_mov_b64 s[44:45], -1
	s_cbranch_scc0 .LBB0_767
	s_waitcnt lgkmcnt(0)
	s_add_u32 s4, s26, 0x9640000
	s_addc_u32 s5, s27, 0
	s_lshl_b32 s38, s70, 1
	s_add_u32 s30, s26, s38
	s_addc_u32 s31, s27, 0
	v_lshlrev_b32_e32 v128, 1, v172
	v_mov_b32_e32 v129, v169
	v_lshl_add_u64 v[130:131], s[30:31], 0, v[128:129]
	s_lshl_b64 s[30:31], s[24:25], 1
	v_add_u32_e32 v132, s54, v192
	v_lshl_add_u64 v[130:131], v[130:131], 0, s[30:31]
	s_mov_b64 s[44:45], 0x1a642000
	v_lshl_add_u64 v[130:131], v[130:131], 0, s[44:45]
	v_or_b32_e32 v133, 16, v132
	v_mad_i64_i32 v[142:143], s[44:45], v133, s37, v[130:131]
	v_or_b32_e32 v133, 32, v132
	v_mad_i64_i32 v[150:151], s[44:45], v133, s37, v[130:131]
	v_or_b32_e32 v133, 48, v132
	v_mad_i64_i32 v[134:135], s[44:45], v132, s37, v[130:131]
	v_mad_i64_i32 v[158:159], s[44:45], v133, s37, v[130:131]
	global_load_dwordx2 v[136:137], v[134:135], off
	global_load_dwordx2 v[138:139], v[134:135], off offset:32
	global_load_dwordx2 v[140:141], v[134:135], off offset:256
	s_nop 0
	global_load_dwordx2 v[134:135], v[134:135], off offset:288
	s_nop 0
	global_load_dwordx2 v[144:145], v[142:143], off
	global_load_dwordx2 v[146:147], v[142:143], off offset:32
	global_load_dwordx2 v[148:149], v[142:143], off offset:256
	s_nop 0
	global_load_dwordx2 v[142:143], v[142:143], off offset:288
	s_nop 0
	global_load_dwordx2 v[152:153], v[150:151], off
	global_load_dwordx2 v[154:155], v[150:151], off offset:32
	global_load_dwordx2 v[156:157], v[150:151], off offset:256
	s_nop 0
	global_load_dwordx2 v[150:151], v[150:151], off offset:288
	s_nop 0
	global_load_dwordx2 v[160:161], v[158:159], off
	global_load_dwordx2 v[162:163], v[158:159], off offset:32
	global_load_dwordx2 v[164:165], v[158:159], off offset:256
	s_nop 0
	global_load_dwordx2 v[158:159], v[158:159], off offset:288
	v_ashrrev_i32_e32 v133, 31, v132
	s_waitcnt vmcnt(0)
	v_lshlrev_b32_e32 v166, 16, v136
	v_and_b32_e32 v136, 0xffff0000, v136
	v_lshlrev_b64 v[132:133], 12, v[132:133]
	v_mul_f32_e32 v166, v124, v166
	v_mul_f32_e32 v136, v125, v136
	v_lshl_add_u64 v[132:133], s[4:5], 0, v[132:133]
	v_cvt_pk_bf16_f32 v136, v166, v136
	v_lshlrev_b32_e32 v166, 16, v137
	v_and_b32_e32 v137, 0xffff0000, v137
	v_lshl_add_u64 v[132:133], v[132:133], 0, s[30:31]
	v_mul_f32_e32 v137, v127, v137
	v_lshl_add_u64 v[132:133], v[132:133], 0, s[38:39]
	v_mul_f32_e32 v166, v126, v166
	v_cvt_pk_bf16_f32 v137, v166, v137
	v_lshl_add_u64 v[132:133], v[132:133], 0, v[128:129]
	global_store_dwordx2 v[132:133], v[136:137], off
	v_lshlrev_b32_e32 v136, 16, v138
	v_and_b32_e32 v137, 0xffff0000, v138
	v_mul_f32_e32 v136, v120, v136
	v_mul_f32_e32 v137, v121, v137
	v_cvt_pk_bf16_f32 v136, v136, v137
	v_lshlrev_b32_e32 v137, 16, v139
	v_mul_f32_e32 v137, v122, v137
	v_and_b32_e32 v138, 0xffff0000, v139
	v_mul_f32_e32 v138, v123, v138
	v_cvt_pk_bf16_f32 v137, v137, v138
	global_store_dwordx2 v[132:133], v[136:137], off offset:32
	v_lshlrev_b32_e32 v136, 16, v140
	v_and_b32_e32 v137, 0xffff0000, v140
	v_mul_f32_e32 v136, v116, v136
	v_mul_f32_e32 v137, v117, v137
	v_cvt_pk_bf16_f32 v136, v136, v137
	v_lshlrev_b32_e32 v137, 16, v141
	v_mul_f32_e32 v137, v118, v137
	v_and_b32_e32 v138, 0xffff0000, v141
	v_mul_f32_e32 v138, v119, v138
	v_cvt_pk_bf16_f32 v137, v137, v138
	global_store_dwordx2 v[132:133], v[136:137], off offset:256
	v_lshlrev_b32_e32 v136, 16, v134
	v_and_b32_e32 v134, 0xffff0000, v134
	v_mul_f32_e32 v136, v112, v136
	v_mul_f32_e32 v134, v113, v134
	v_cvt_pk_bf16_f32 v134, v136, v134
	v_lshlrev_b32_e32 v136, 16, v135
	v_and_b32_e32 v135, 0xffff0000, v135
	v_mul_f32_e32 v135, v115, v135
	v_mul_f32_e32 v136, v114, v136
	v_cvt_pk_bf16_f32 v135, v136, v135
	global_store_dwordx2 v[132:133], v[134:135], off offset:288
	v_lshlrev_b32_e32 v132, 16, v144
	v_and_b32_e32 v133, 0xffff0000, v144
	v_mul_f32_e32 v132, v108, v132
	v_mul_f32_e32 v133, v109, v133
	v_cvt_pk_bf16_f32 v132, v132, v133
	v_lshlrev_b32_e32 v133, 16, v145
	v_and_b32_e32 v134, 0xffff0000, v145
	v_mul_f32_e32 v133, v110, v133
	v_mul_f32_e32 v134, v111, v134
	v_cvt_pk_bf16_f32 v133, v133, v134
	v_add_u32_e32 v134, s54, v194
	v_ashrrev_i32_e32 v135, 31, v134
	v_lshlrev_b64 v[134:135], 12, v[134:135]
	v_lshl_add_u64 v[134:135], s[4:5], 0, v[134:135]
	v_lshl_add_u64 v[134:135], v[134:135], 0, s[30:31]
	v_lshl_add_u64 v[134:135], v[134:135], 0, s[38:39]
	v_lshl_add_u64 v[134:135], v[134:135], 0, v[128:129]
	global_store_dwordx2 v[134:135], v[132:133], off
	v_lshlrev_b32_e32 v132, 16, v146
	v_and_b32_e32 v133, 0xffff0000, v146
	v_mul_f32_e32 v132, v104, v132
	v_mul_f32_e32 v133, v105, v133
	v_cvt_pk_bf16_f32 v132, v132, v133
	v_lshlrev_b32_e32 v133, 16, v147
	v_mul_f32_e32 v133, v106, v133
	v_and_b32_e32 v136, 0xffff0000, v147
	v_mul_f32_e32 v136, v107, v136
	v_cvt_pk_bf16_f32 v133, v133, v136
	global_store_dwordx2 v[134:135], v[132:133], off offset:32
	v_lshlrev_b32_e32 v132, 16, v148
	v_and_b32_e32 v133, 0xffff0000, v148
	v_mul_f32_e32 v132, v100, v132
	v_mul_f32_e32 v133, v101, v133
	v_cvt_pk_bf16_f32 v132, v132, v133
	v_lshlrev_b32_e32 v133, 16, v149
	v_mul_f32_e32 v133, v102, v133
	v_and_b32_e32 v136, 0xffff0000, v149
	v_mul_f32_e32 v136, v103, v136
	v_cvt_pk_bf16_f32 v133, v133, v136
	global_store_dwordx2 v[134:135], v[132:133], off offset:256
	v_lshlrev_b32_e32 v132, 16, v142
	v_and_b32_e32 v133, 0xffff0000, v142
	v_mul_f32_e32 v132, v96, v132
	v_mul_f32_e32 v133, v97, v133
	v_cvt_pk_bf16_f32 v132, v132, v133
	v_lshlrev_b32_e32 v133, 16, v143
	v_mul_f32_e32 v133, v98, v133
	v_and_b32_e32 v136, 0xffff0000, v143
	v_mul_f32_e32 v136, v99, v136
	v_cvt_pk_bf16_f32 v133, v133, v136
	global_store_dwordx2 v[134:135], v[132:133], off offset:288
	v_lshlrev_b32_e32 v132, 16, v152
	v_and_b32_e32 v133, 0xffff0000, v152
	v_mul_f32_e32 v132, v92, v132
	v_mul_f32_e32 v133, v93, v133
	v_cvt_pk_bf16_f32 v132, v132, v133
	v_lshlrev_b32_e32 v133, 16, v153
	v_and_b32_e32 v134, 0xffff0000, v153
	v_mul_f32_e32 v133, v94, v133
	v_mul_f32_e32 v134, v95, v134
	v_cvt_pk_bf16_f32 v133, v133, v134
	v_add_u32_e32 v134, s54, v195
	v_ashrrev_i32_e32 v135, 31, v134
	v_lshlrev_b64 v[134:135], 12, v[134:135]
	v_lshl_add_u64 v[134:135], s[4:5], 0, v[134:135]
	v_lshl_add_u64 v[134:135], v[134:135], 0, s[30:31]
	v_lshl_add_u64 v[134:135], v[134:135], 0, s[38:39]
	v_lshl_add_u64 v[134:135], v[134:135], 0, v[128:129]
	global_store_dwordx2 v[134:135], v[132:133], off
	v_lshlrev_b32_e32 v132, 16, v154
	v_and_b32_e32 v133, 0xffff0000, v154
	v_mul_f32_e32 v132, v88, v132
	v_mul_f32_e32 v133, v89, v133
	v_cvt_pk_bf16_f32 v132, v132, v133
	v_lshlrev_b32_e32 v133, 16, v155
	v_mul_f32_e32 v133, v90, v133
	v_and_b32_e32 v136, 0xffff0000, v155
	v_mul_f32_e32 v136, v91, v136
	v_cvt_pk_bf16_f32 v133, v133, v136
	global_store_dwordx2 v[134:135], v[132:133], off offset:32
	v_lshlrev_b32_e32 v132, 16, v156
	v_and_b32_e32 v133, 0xffff0000, v156
	v_mul_f32_e32 v132, v84, v132
	v_mul_f32_e32 v133, v85, v133
	v_cvt_pk_bf16_f32 v132, v132, v133
	v_lshlrev_b32_e32 v133, 16, v157
	v_mul_f32_e32 v133, v86, v133
	v_and_b32_e32 v136, 0xffff0000, v157
	v_mul_f32_e32 v136, v87, v136
	v_cvt_pk_bf16_f32 v133, v133, v136
	global_store_dwordx2 v[134:135], v[132:133], off offset:256
	v_lshlrev_b32_e32 v132, 16, v150
	v_and_b32_e32 v133, 0xffff0000, v150
	v_mul_f32_e32 v132, v80, v132
	v_mul_f32_e32 v133, v81, v133
	v_cvt_pk_bf16_f32 v132, v132, v133
	v_lshlrev_b32_e32 v133, 16, v151
	v_mul_f32_e32 v133, v82, v133
	v_and_b32_e32 v136, 0xffff0000, v151
	v_mul_f32_e32 v136, v83, v136
	v_cvt_pk_bf16_f32 v133, v133, v136
	global_store_dwordx2 v[134:135], v[132:133], off offset:288
	v_lshlrev_b32_e32 v132, 16, v160
	v_and_b32_e32 v133, 0xffff0000, v160
	v_mul_f32_e32 v132, v76, v132
	v_mul_f32_e32 v133, v77, v133
	v_cvt_pk_bf16_f32 v132, v132, v133
	v_lshlrev_b32_e32 v133, 16, v161
	v_and_b32_e32 v134, 0xffff0000, v161
	v_mul_f32_e32 v133, v78, v133
	v_mul_f32_e32 v134, v79, v134
	v_cvt_pk_bf16_f32 v133, v133, v134
	v_add_u32_e32 v134, s54, v196
	v_ashrrev_i32_e32 v135, 31, v134
	v_lshlrev_b64 v[134:135], 12, v[134:135]
	v_lshl_add_u64 v[134:135], s[4:5], 0, v[134:135]
	v_lshl_add_u64 v[134:135], v[134:135], 0, s[30:31]
	v_lshl_add_u64 v[134:135], v[134:135], 0, s[38:39]
	v_lshl_add_u64 v[134:135], v[134:135], 0, v[128:129]
	global_store_dwordx2 v[134:135], v[132:133], off
	v_lshlrev_b32_e32 v132, 16, v162
	v_and_b32_e32 v133, 0xffff0000, v162
	v_mul_f32_e32 v132, v72, v132
	v_mul_f32_e32 v133, v73, v133
	v_cvt_pk_bf16_f32 v132, v132, v133
	v_lshlrev_b32_e32 v133, 16, v163
	v_mul_f32_e32 v133, v74, v133
	v_and_b32_e32 v136, 0xffff0000, v163
	v_mul_f32_e32 v136, v75, v136
	v_cvt_pk_bf16_f32 v133, v133, v136
	global_store_dwordx2 v[134:135], v[132:133], off offset:32
	v_lshlrev_b32_e32 v132, 16, v164
	v_and_b32_e32 v133, 0xffff0000, v164
	v_mul_f32_e32 v132, v68, v132
	v_mul_f32_e32 v133, v69, v133
	v_cvt_pk_bf16_f32 v132, v132, v133
	v_lshlrev_b32_e32 v133, 16, v165
	v_mul_f32_e32 v133, v70, v133
	v_and_b32_e32 v136, 0xffff0000, v165
	v_mul_f32_e32 v136, v71, v136
	v_cvt_pk_bf16_f32 v133, v133, v136
	global_store_dwordx2 v[134:135], v[132:133], off offset:256
	v_lshlrev_b32_e32 v132, 16, v158
	v_and_b32_e32 v133, 0xffff0000, v158
	v_mul_f32_e32 v132, v64, v132
	v_mul_f32_e32 v133, v65, v133
	v_cvt_pk_bf16_f32 v132, v132, v133
	v_lshlrev_b32_e32 v133, 16, v159
	v_mul_f32_e32 v133, v66, v133
	v_and_b32_e32 v136, 0xffff0000, v159
	v_mul_f32_e32 v136, v67, v136
	v_cvt_pk_bf16_f32 v133, v133, v136
	global_store_dwordx2 v[134:135], v[132:133], off offset:288
	v_add_u32_e32 v132, s54, v197
	v_or_b32_e32 v133, 16, v132
	v_mad_i64_i32 v[142:143], s[44:45], v133, s37, v[130:131]
	v_or_b32_e32 v133, 32, v132
	v_mad_i64_i32 v[150:151], s[44:45], v133, s37, v[130:131]
	v_or_b32_e32 v133, 48, v132
	v_mad_i64_i32 v[134:135], s[44:45], v132, s37, v[130:131]
	v_mad_i64_i32 v[130:131], s[44:45], v133, s37, v[130:131]
	global_load_dwordx2 v[136:137], v[134:135], off
	global_load_dwordx2 v[138:139], v[134:135], off offset:32
	global_load_dwordx2 v[140:141], v[134:135], off offset:256
	s_nop 0
	global_load_dwordx2 v[134:135], v[134:135], off offset:288
	s_nop 0
	global_load_dwordx2 v[144:145], v[142:143], off
	global_load_dwordx2 v[146:147], v[142:143], off offset:32
	global_load_dwordx2 v[148:149], v[142:143], off offset:256
	s_nop 0
	global_load_dwordx2 v[142:143], v[142:143], off offset:288
	s_nop 0
	global_load_dwordx2 v[152:153], v[150:151], off
	global_load_dwordx2 v[154:155], v[150:151], off offset:32
	global_load_dwordx2 v[156:157], v[150:151], off offset:256
	s_nop 0
	global_load_dwordx2 v[150:151], v[150:151], off offset:288
	s_nop 0
	global_load_dwordx2 v[158:159], v[130:131], off
	global_load_dwordx2 v[160:161], v[130:131], off offset:32
	global_load_dwordx2 v[162:163], v[130:131], off offset:256
	s_nop 0
	global_load_dwordx2 v[130:131], v[130:131], off offset:288
	v_ashrrev_i32_e32 v133, 31, v132
	s_waitcnt vmcnt(15)
	v_lshlrev_b32_e32 v164, 16, v136
	v_and_b32_e32 v136, 0xffff0000, v136
	v_lshlrev_b64 v[132:133], 12, v[132:133]
	v_mul_f32_e32 v164, v60, v164
	v_mul_f32_e32 v136, v61, v136
	v_lshl_add_u64 v[132:133], s[4:5], 0, v[132:133]
	v_cvt_pk_bf16_f32 v136, v164, v136
	v_lshlrev_b32_e32 v164, 16, v137
	v_and_b32_e32 v137, 0xffff0000, v137
	v_lshl_add_u64 v[132:133], v[132:133], 0, s[30:31]
	v_mul_f32_e32 v137, v63, v137
	v_lshl_add_u64 v[132:133], v[132:133], 0, s[38:39]
	v_mul_f32_e32 v164, v62, v164
	v_cvt_pk_bf16_f32 v137, v164, v137
	v_lshl_add_u64 v[132:133], v[132:133], 0, v[128:129]
	global_store_dwordx2 v[132:133], v[136:137], off
	s_waitcnt vmcnt(15)
	v_lshlrev_b32_e32 v136, 16, v138
	v_and_b32_e32 v137, 0xffff0000, v138
	v_mul_f32_e32 v136, v56, v136
	v_mul_f32_e32 v137, v57, v137
	v_cvt_pk_bf16_f32 v136, v136, v137
	v_lshlrev_b32_e32 v137, 16, v139
	v_mul_f32_e32 v137, v58, v137
	v_and_b32_e32 v138, 0xffff0000, v139
	v_mul_f32_e32 v138, v59, v138
	v_cvt_pk_bf16_f32 v137, v137, v138
	global_store_dwordx2 v[132:133], v[136:137], off offset:32
	s_waitcnt vmcnt(15)
	v_lshlrev_b32_e32 v136, 16, v140
	v_and_b32_e32 v137, 0xffff0000, v140
	v_mul_f32_e32 v136, v52, v136
	v_mul_f32_e32 v137, v53, v137
	v_cvt_pk_bf16_f32 v136, v136, v137
	v_lshlrev_b32_e32 v137, 16, v141
	v_mul_f32_e32 v137, v54, v137
	v_and_b32_e32 v138, 0xffff0000, v141
	v_mul_f32_e32 v138, v55, v138
	v_cvt_pk_bf16_f32 v137, v137, v138
	global_store_dwordx2 v[132:133], v[136:137], off offset:256
	s_waitcnt vmcnt(15)
	v_lshlrev_b32_e32 v136, 16, v134
	v_and_b32_e32 v134, 0xffff0000, v134
	v_mul_f32_e32 v136, v48, v136
	v_mul_f32_e32 v134, v49, v134
	v_cvt_pk_bf16_f32 v134, v136, v134
	v_lshlrev_b32_e32 v136, 16, v135
	v_and_b32_e32 v135, 0xffff0000, v135
	v_mul_f32_e32 v135, v51, v135
	v_mul_f32_e32 v136, v50, v136
	v_cvt_pk_bf16_f32 v135, v136, v135
	global_store_dwordx2 v[132:133], v[134:135], off offset:288
	s_waitcnt vmcnt(15)
	v_lshlrev_b32_e32 v132, 16, v144
	v_and_b32_e32 v133, 0xffff0000, v144
	v_mul_f32_e32 v132, v44, v132
	v_mul_f32_e32 v133, v45, v133
	v_cvt_pk_bf16_f32 v132, v132, v133
	v_lshlrev_b32_e32 v133, 16, v145
	v_and_b32_e32 v134, 0xffff0000, v145
	v_mul_f32_e32 v133, v46, v133
	v_mul_f32_e32 v134, v47, v134
	v_cvt_pk_bf16_f32 v133, v133, v134
	v_add_u32_e32 v134, s54, v198
	v_ashrrev_i32_e32 v135, 31, v134
	v_lshlrev_b64 v[134:135], 12, v[134:135]
	v_lshl_add_u64 v[134:135], s[4:5], 0, v[134:135]
	v_lshl_add_u64 v[134:135], v[134:135], 0, s[30:31]
	v_lshl_add_u64 v[134:135], v[134:135], 0, s[38:39]
	v_lshl_add_u64 v[134:135], v[134:135], 0, v[128:129]
	global_store_dwordx2 v[134:135], v[132:133], off
	s_waitcnt vmcnt(15)
	v_lshlrev_b32_e32 v132, 16, v146
	v_and_b32_e32 v133, 0xffff0000, v146
	v_mul_f32_e32 v132, v40, v132
	v_mul_f32_e32 v133, v41, v133
	v_cvt_pk_bf16_f32 v132, v132, v133
	v_lshlrev_b32_e32 v133, 16, v147
	v_mul_f32_e32 v133, v42, v133
	v_and_b32_e32 v136, 0xffff0000, v147
	v_mul_f32_e32 v136, v43, v136
	v_cvt_pk_bf16_f32 v133, v133, v136
	global_store_dwordx2 v[134:135], v[132:133], off offset:32
	s_waitcnt vmcnt(15)
	v_lshlrev_b32_e32 v132, 16, v148
	v_and_b32_e32 v133, 0xffff0000, v148
	v_mul_f32_e32 v132, v36, v132
	v_mul_f32_e32 v133, v37, v133
	v_cvt_pk_bf16_f32 v132, v132, v133
	v_lshlrev_b32_e32 v133, 16, v149
	v_mul_f32_e32 v133, v38, v133
	v_and_b32_e32 v136, 0xffff0000, v149
	v_mul_f32_e32 v136, v39, v136
	v_cvt_pk_bf16_f32 v133, v133, v136
	global_store_dwordx2 v[134:135], v[132:133], off offset:256
	s_waitcnt vmcnt(15)
	v_lshlrev_b32_e32 v132, 16, v142
	v_and_b32_e32 v133, 0xffff0000, v142
	v_mul_f32_e32 v132, v32, v132
	v_mul_f32_e32 v133, v33, v133
	v_cvt_pk_bf16_f32 v132, v132, v133
	v_lshlrev_b32_e32 v133, 16, v143
	v_mul_f32_e32 v133, v34, v133
	v_and_b32_e32 v136, 0xffff0000, v143
	v_mul_f32_e32 v136, v35, v136
	v_cvt_pk_bf16_f32 v133, v133, v136
	global_store_dwordx2 v[134:135], v[132:133], off offset:288
	s_waitcnt vmcnt(15)
	v_lshlrev_b32_e32 v132, 16, v152
	v_and_b32_e32 v133, 0xffff0000, v152
	v_mul_f32_e32 v132, v28, v132
	v_mul_f32_e32 v133, v29, v133
	v_cvt_pk_bf16_f32 v132, v132, v133
	v_lshlrev_b32_e32 v133, 16, v153
	v_and_b32_e32 v134, 0xffff0000, v153
	v_mul_f32_e32 v133, v30, v133
	v_mul_f32_e32 v134, v31, v134
	v_cvt_pk_bf16_f32 v133, v133, v134
	v_add_u32_e32 v134, s54, v199
	v_ashrrev_i32_e32 v135, 31, v134
	v_lshlrev_b64 v[134:135], 12, v[134:135]
	v_lshl_add_u64 v[134:135], s[4:5], 0, v[134:135]
	v_lshl_add_u64 v[134:135], v[134:135], 0, s[30:31]
	v_lshl_add_u64 v[134:135], v[134:135], 0, s[38:39]
	v_lshl_add_u64 v[134:135], v[134:135], 0, v[128:129]
	global_store_dwordx2 v[134:135], v[132:133], off
	s_waitcnt vmcnt(15)
	v_lshlrev_b32_e32 v132, 16, v154
	v_and_b32_e32 v133, 0xffff0000, v154
	v_mul_f32_e32 v132, v24, v132
	v_mul_f32_e32 v133, v25, v133
	v_cvt_pk_bf16_f32 v132, v132, v133
	v_lshlrev_b32_e32 v133, 16, v155
	v_mul_f32_e32 v133, v26, v133
	v_and_b32_e32 v136, 0xffff0000, v155
	v_mul_f32_e32 v136, v27, v136
	v_cvt_pk_bf16_f32 v133, v133, v136
	global_store_dwordx2 v[134:135], v[132:133], off offset:32
	s_waitcnt vmcnt(15)
	v_lshlrev_b32_e32 v132, 16, v156
	v_and_b32_e32 v133, 0xffff0000, v156
	v_mul_f32_e32 v132, v20, v132
	v_mul_f32_e32 v133, v21, v133
	v_cvt_pk_bf16_f32 v132, v132, v133
	v_lshlrev_b32_e32 v133, 16, v157
	v_mul_f32_e32 v133, v22, v133
	v_and_b32_e32 v136, 0xffff0000, v157
	v_mul_f32_e32 v136, v23, v136
	v_cvt_pk_bf16_f32 v133, v133, v136
	global_store_dwordx2 v[134:135], v[132:133], off offset:256
	s_waitcnt vmcnt(15)
	v_lshlrev_b32_e32 v132, 16, v150
	v_and_b32_e32 v133, 0xffff0000, v150
	v_mul_f32_e32 v132, v16, v132
	v_mul_f32_e32 v133, v17, v133
	v_cvt_pk_bf16_f32 v132, v132, v133
	v_lshlrev_b32_e32 v133, 16, v151
	v_mul_f32_e32 v133, v18, v133
	v_and_b32_e32 v136, 0xffff0000, v151
	v_mul_f32_e32 v136, v19, v136
	v_cvt_pk_bf16_f32 v133, v133, v136
	global_store_dwordx2 v[134:135], v[132:133], off offset:288
	s_waitcnt vmcnt(15)
	v_lshlrev_b32_e32 v132, 16, v158
	v_and_b32_e32 v133, 0xffff0000, v158
	v_mul_f32_e32 v132, v12, v132
	v_mul_f32_e32 v133, v13, v133
	v_cvt_pk_bf16_f32 v132, v132, v133
	v_lshlrev_b32_e32 v133, 16, v159
	v_and_b32_e32 v134, 0xffff0000, v159
	v_mul_f32_e32 v133, v14, v133
	v_mul_f32_e32 v134, v15, v134
	v_cvt_pk_bf16_f32 v133, v133, v134
	v_add_u32_e32 v134, s54, v200
	v_ashrrev_i32_e32 v135, 31, v134
	v_lshlrev_b64 v[134:135], 12, v[134:135]
	v_lshl_add_u64 v[134:135], s[4:5], 0, v[134:135]
	v_lshl_add_u64 v[134:135], v[134:135], 0, s[30:31]
	v_lshl_add_u64 v[134:135], v[134:135], 0, s[38:39]
	v_lshl_add_u64 v[128:129], v[134:135], 0, v[128:129]
	global_store_dwordx2 v[128:129], v[132:133], off
	s_waitcnt vmcnt(15)
	v_lshlrev_b32_e32 v132, 16, v160
	v_and_b32_e32 v133, 0xffff0000, v160
	v_mul_f32_e32 v132, v8, v132
	v_mul_f32_e32 v133, v9, v133
	v_cvt_pk_bf16_f32 v132, v132, v133
	v_lshlrev_b32_e32 v133, 16, v161
	v_mul_f32_e32 v133, v10, v133
	v_and_b32_e32 v134, 0xffff0000, v161
	v_mul_f32_e32 v134, v11, v134
	v_cvt_pk_bf16_f32 v133, v133, v134
	global_store_dwordx2 v[128:129], v[132:133], off offset:32
	s_waitcnt vmcnt(15)
	v_lshlrev_b32_e32 v132, 16, v162
	v_and_b32_e32 v133, 0xffff0000, v162
	v_mul_f32_e32 v132, v4, v132
	v_mul_f32_e32 v133, v5, v133
	v_cvt_pk_bf16_f32 v132, v132, v133
	v_lshlrev_b32_e32 v133, 16, v163
	v_mul_f32_e32 v133, v6, v133
	v_and_b32_e32 v134, 0xffff0000, v163
	v_mul_f32_e32 v134, v7, v134
	v_cvt_pk_bf16_f32 v133, v133, v134
	global_store_dwordx2 v[128:129], v[132:133], off offset:256
	s_waitcnt vmcnt(15)
	v_lshlrev_b32_e32 v132, 16, v130
	v_and_b32_e32 v130, 0xffff0000, v130
	v_mul_f32_e32 v132, v0, v132
	v_mul_f32_e32 v130, v1, v130
	v_cvt_pk_bf16_f32 v130, v132, v130
	v_lshlrev_b32_e32 v132, 16, v131
	v_and_b32_e32 v131, 0xffff0000, v131
	v_mul_f32_e32 v131, v3, v131
	v_mul_f32_e32 v132, v2, v132
	v_cvt_pk_bf16_f32 v131, v132, v131
	global_store_dwordx2 v[128:129], v[130:131], off offset:288
	s_mov_b64 s[44:45], 0
